# QKV K-loop: per-iteration vmcnt(0) drain hoisted out of the loop; tile-top vmcnt(0) store drains dropped in 4 GEMM instances
# baseline (speedup 1.0000x reference)
; #define PG8_STAGE(bufoff, gbase, voff) do { _Pragma("unroll") for (int _i = 0; _i < 2; ++_i) \
;         __builtin_amdgcn_global_load_lds((const unsigned*)((const char*)(gbase) + (voff)[_i]), (PG8_LAS unsigned*)(lds + (bufoff) + ldsw + _i * 8192), 16, 0, 0); } while (0)
; #define PG8_LDA(dst, b, h) do { _Pragma("unroll") for (int m = 0; m < 4; ++m) _Pragma("unroll") for (int k = 0; k < 2; ++k) dst[m][k] = *(const PG8_LAS bf16x8*)(lds + PG8_SA(b, h) + aoff + m * 2048 + k * 1024); } while (0)
; #define PG8_LDB(dst, b, h) do { _Pragma("unroll") for (int n = 0; n < 2; ++n) _Pragma("unroll") for (int k = 0; k < 2; ++k) dst[n][k] = *(const PG8_LAS bf16x8*)(lds + PG8_SB(b, h) + boff + n * 2048 + k * 1024); } while (0)
; #define PG8_MMA(ai, bj, At, Bt) do { __builtin_amdgcn_s_setprio(1); _Pragma("unroll") for (int m = 0; m < 4; ++m) _Pragma("unroll") for (int n = 0; n < 2; ++n) _Pragma("unroll") for (int k = 0; k < 2; ++k) \
;         acc[ai][bj][m][n] = __builtin_amdgcn_mfma_f32_16x16x32_bf16(Bt[n][k], At[m][k], acc[ai][bj][m][n], 0, 0, 0); __builtin_amdgcn_s_setprio(0); } while (0)
; #define PG8_WAIT_V(n) asm volatile("s_waitcnt vmcnt(" #n ")" ::: "memory")
; #define PG8_WAIT_L(n) asm volatile("s_waitcnt lgkmcnt(" #n ")" ::: "memory")
; #define PG8_BAR __builtin_amdgcn_s_barrier()
; #define PG8_SCHED __builtin_amdgcn_sched_barrier(0)
; template <class Epi, class Sched, bool ALIGN_EPI = false, bool SP2 = false>
; __device__ __forceinline__ void gemm_phase(PG8_LAS unsigned char* lds, const Gemm g, const Sched& S, const Epi& E) {
;     ...
;         for (int t = 0; t < nt; t += 2) {
;             const bool last = (t == nt - 2);
;             const char* a1 = cA + (size_t)(t + 1) * kstep;
;             const char* a2 = last ? nA : cA + (size_t)(t + 2) * kstep; const char* b2 = last ? nB : cB + (size_t)(t + 2) * kstep;
;             const char* a3 = a2 + kstep; const char* b3 = b2 + kstep;
;             if (last && has_next) S.a_ready(nxt);
;             if constexpr (SP2) {
;             PG8_LDB(B0, 0, 0); PG8_LDB(B1, 0, 1); PG8_SCHED; PG8_LDA(At, 0, 0); PG8_STAGE(PG8_SA(1, 1), a1 + hstepA, voffA);
;             PG8_WAIT_V(8); PG8_WAIT_L(0); PG8_BAR; PG8_MMA(0, 0, At, B0); PG8_MMA(0, 1, At, B1); PG8_BAR; PG8_SCHED;
;             PG8_LDA(At, 0, 1); PG8_STAGE(PG8_SB(0, 0), b2, voffB); PG8_STAGE(PG8_SB(0, 1), b2 + hstepB, voffB); PG8_STAGE(PG8_SA(0, 0), a2, voffA);
.LBB0_171:
	s_add_u32 s50, s8, 0xfffc0080
	s_addc_u32 s51, s9, -1
	s_add_i32 s60, 0, 0x10000
	s_cmp_eq_u32 s59, 12
	s_cselect_b32 s53, s11, s51
	s_cselect_b32 s52, s37, s50
	s_cselect_b32 s51, s35, s58
	s_cselect_b32 s50, s54, s55
	s_add_i32 s62, 0, 0x14000
	v_add_u32_e32 v76, s60, v162
	v_add_u32_e32 v158, s62, v162
	ds_read_b128 v[64:67], v76
	ds_read_b128 v[68:71], v76 offset:1024
	ds_read_b128 v[72:75], v76 offset:2048
	ds_read_b128 v[76:79], v76 offset:3072
	ds_read_b128 v[154:157], v158
	ds_read_b128 v[164:167], v158 offset:1024
	ds_read_b128 v[168:171], v158 offset:2048
	ds_read_b128 v[172:175], v158 offset:3072
	v_lshl_add_u64 v[158:159], s[8:9], 0, v[150:151]
	s_add_i32 m0, s57, 0xc000
	ds_read_b128 v[176:179], v163
	ds_read_b128 v[180:183], v163 offset:1024
	ds_read_b128 v[184:187], v163 offset:2048
	ds_read_b128 v[194:197], v163 offset:3072
	ds_read_b128 v[230:233], v163 offset:4096
	ds_read_b128 v[234:237], v163 offset:5120
	ds_read_b128 v[238:241], v163 offset:6144
	ds_read_b128 v[242:245], v163 offset:7168
	global_load_lds_dwordx4 v[158:159], off
	v_lshl_add_u64 v[158:159], s[8:9], 0, v[152:153]
	s_add_i32 m0, s57, 0xe000
	s_nop 0
	global_load_lds_dwordx4 v[158:159], off
	s_waitcnt vmcnt(8)
	s_waitcnt lgkmcnt(0)
	s_barrier
	s_setprio 1
	s_waitcnt lgkmcnt(0)
	v_mfma_f32_16x16x32_bf16 v[140:143], v[64:67], v[176:179], v[140:143]
	v_mfma_f32_16x16x32_bf16 v[136:139], v[72:75], v[176:179], v[136:139]
	v_mfma_f32_16x16x32_bf16 v[124:127], v[64:67], v[184:187], v[124:127]
	v_mfma_f32_16x16x32_bf16 v[120:123], v[72:75], v[184:187], v[120:123]
	v_mfma_f32_16x16x32_bf16 v[108:111], v[64:67], v[230:233], v[108:111]
	v_mfma_f32_16x16x32_bf16 v[104:107], v[72:75], v[230:233], v[104:107]
	v_mfma_f32_16x16x32_bf16 v[92:95], v[64:67], v[238:241], v[92:95]
	v_mfma_f32_16x16x32_bf16 v[88:91], v[72:75], v[238:241], v[88:91]
	v_mfma_f32_16x16x32_bf16 v[140:143], v[68:71], v[180:183], v[140:143]
	v_mfma_f32_16x16x32_bf16 v[136:139], v[76:79], v[180:183], v[136:139]
	v_mfma_f32_16x16x32_bf16 v[124:127], v[68:71], v[194:197], v[124:127]
	v_mfma_f32_16x16x32_bf16 v[120:123], v[76:79], v[194:197], v[120:123]
	v_mfma_f32_16x16x32_bf16 v[108:111], v[68:71], v[234:237], v[108:111]
	v_mfma_f32_16x16x32_bf16 v[104:107], v[76:79], v[234:237], v[104:107]
	v_mfma_f32_16x16x32_bf16 v[92:95], v[68:71], v[242:245], v[92:95]
	v_mfma_f32_16x16x32_bf16 v[88:91], v[76:79], v[242:245], v[88:91]
	s_setprio 0
	s_setprio 1
	v_mfma_f32_16x16x32_bf16 v[132:135], v[154:157], v[176:179], v[132:135]
	v_mfma_f32_16x16x32_bf16 v[128:131], v[168:171], v[176:179], v[128:131]
	v_mfma_f32_16x16x32_bf16 v[116:119], v[154:157], v[184:187], v[116:119]
	v_mfma_f32_16x16x32_bf16 v[112:115], v[168:171], v[184:187], v[112:115]
	v_mfma_f32_16x16x32_bf16 v[100:103], v[154:157], v[230:233], v[100:103]
	v_mfma_f32_16x16x32_bf16 v[96:99], v[168:171], v[230:233], v[96:99]
	v_mfma_f32_16x16x32_bf16 v[84:87], v[154:157], v[238:241], v[84:87]
	v_mfma_f32_16x16x32_bf16 v[80:83], v[168:171], v[238:241], v[80:83]
	v_mfma_f32_16x16x32_bf16 v[132:135], v[164:167], v[180:183], v[132:135]
	v_mfma_f32_16x16x32_bf16 v[128:131], v[172:175], v[180:183], v[128:131]
	v_mfma_f32_16x16x32_bf16 v[116:119], v[164:167], v[194:197], v[116:119]
	v_mfma_f32_16x16x32_bf16 v[112:115], v[172:175], v[194:197], v[112:115]
	v_mfma_f32_16x16x32_bf16 v[100:103], v[164:167], v[234:237], v[100:103]
	v_mfma_f32_16x16x32_bf16 v[96:99], v[172:175], v[234:237], v[96:99]
	v_mfma_f32_16x16x32_bf16 v[84:87], v[164:167], v[242:245], v[84:87]
	v_mfma_f32_16x16x32_bf16 v[80:83], v[172:175], v[242:245], v[80:83]
	s_setprio 0
	s_barrier
	s_add_i32 s60, s60, s69
	v_lshl_add_u64 v[158:159], s[50:51], 0, v[188:189]
	s_mov_b32 m0, s60
	ds_read_b128 v[176:179], v163 offset:16384
	ds_read_b128 v[180:183], v163 offset:17408
	ds_read_b128 v[184:187], v163 offset:18432
	ds_read_b128 v[194:197], v163 offset:19456
	ds_read_b128 v[230:233], v163 offset:20480
	ds_read_b128 v[234:237], v163 offset:21504
	ds_read_b128 v[238:241], v163 offset:22528
	ds_read_b128 v[242:245], v163 offset:23552
	global_load_lds_dwordx4 v[158:159], off
	s_add_i32 m0, s60, 0x2000
	s_add_u32 s60, s50, 0x40000
	v_lshl_add_u64 v[246:247], s[50:51], 0, v[148:149]
	s_addc_u32 s61, s51, 0
	s_add_i32 s62, s62, s69
	global_load_lds_dwordx4 v[246:247], off
	v_lshl_add_u64 v[248:249], s[60:61], 0, v[188:189]
	s_mov_b32 m0, s62
	v_lshl_add_u64 v[250:251], s[52:53], 0, v[146:147]
	global_load_lds_dwordx4 v[248:249], off
	v_lshl_add_u64 v[248:249], s[60:61], 0, v[148:149]
	s_add_i32 m0, s62, 0x2000
	s_nop 0
	global_load_lds_dwordx4 v[248:249], off
	v_lshl_add_u64 v[248:249], s[52:53], 0, v[144:145]
	s_mov_b32 m0, s57
	s_nop 0
	global_load_lds_dwordx4 v[248:249], off
	s_mov_b32 m0, s78
	s_nop 0
	global_load_lds_dwordx4 v[250:251], off
	s_waitcnt vmcnt(8)
	s_waitcnt lgkmcnt(0)
	s_barrier
; #define PG8_STAGE(bufoff, gbase, voff) do { _Pragma("unroll") for (int _i = 0; _i < 2; ++_i) \
;         __builtin_amdgcn_global_load_lds((const unsigned*)((const char*)(gbase) + (voff)[_i]), (PG8_LAS unsigned*)(lds + (bufoff) + ldsw + _i * 8192), 16, 0, 0); } while (0)
; #define PG8_LDA(dst, b, h) do { _Pragma("unroll") for (int m = 0; m < 4; ++m) _Pragma("unroll") for (int k = 0; k < 2; ++k) dst[m][k] = *(const PG8_LAS bf16x8*)(lds + PG8_SA(b, h) + aoff + m * 2048 + k * 1024); } while (0)
; #define PG8_LDB(dst, b, h) do { _Pragma("unroll") for (int n = 0; n < 2; ++n) _Pragma("unroll") for (int k = 0; k < 2; ++k) dst[n][k] = *(const PG8_LAS bf16x8*)(lds + PG8_SB(b, h) + boff + n * 2048 + k * 1024); } while (0)
; #define PG8_MMA(ai, bj, At, Bt) do { __builtin_amdgcn_s_setprio(1); _Pragma("unroll") for (int m = 0; m < 4; ++m) _Pragma("unroll") for (int n = 0; n < 2; ++n) _Pragma("unroll") for (int k = 0; k < 2; ++k) \
;         acc[ai][bj][m][n] = __builtin_amdgcn_mfma_f32_16x16x32_bf16(Bt[n][k], At[m][k], acc[ai][bj][m][n], 0, 0, 0); __builtin_amdgcn_s_setprio(0); } while (0)
; #define PG8_WAIT_V(n) asm volatile("s_waitcnt vmcnt(" #n ")" ::: "memory")
; #define PG8_WAIT_L(n) asm volatile("s_waitcnt lgkmcnt(" #n ")" ::: "memory")
; #define PG8_BAR __builtin_amdgcn_s_barrier()
; #define PG8_SCHED __builtin_amdgcn_sched_barrier(0)
; template <class Epi, class Sched, bool ALIGN_EPI = false, bool SP2 = false>
; __device__ __forceinline__ void gemm_phase(PG8_LAS unsigned char* lds, const Gemm g, const Sched& S, const Epi& E) {
;     ...
;             PG8_WAIT_V(8); PG8_WAIT_L(0); PG8_BAR; PG8_MMA(1, 0, At, B0); PG8_MMA(1, 1, At, B1); PG8_BAR; PG8_SCHED;
;             PG8_LDB(B0, 1, 0); PG8_LDB(B1, 1, 1); PG8_SCHED; PG8_LDA(At, 1, 0); PG8_STAGE(PG8_SA(0, 1), a2 + hstepA, voffA);
;             PG8_WAIT_V(8); PG8_WAIT_L(0); PG8_BAR; PG8_MMA(0, 0, At, B0); PG8_MMA(0, 1, At, B1); PG8_BAR; PG8_SCHED;
	s_setprio 1
	s_waitcnt lgkmcnt(0)
	v_mfma_f32_16x16x32_bf16 v[60:63], v[64:67], v[176:179], v[60:63]
	v_mfma_f32_16x16x32_bf16 v[56:59], v[72:75], v[176:179], v[56:59]
	v_mfma_f32_16x16x32_bf16 v[44:47], v[64:67], v[184:187], v[44:47]
	v_mfma_f32_16x16x32_bf16 v[40:43], v[72:75], v[184:187], v[40:43]
	v_mfma_f32_16x16x32_bf16 v[28:31], v[64:67], v[230:233], v[28:31]
	v_mfma_f32_16x16x32_bf16 v[24:27], v[72:75], v[230:233], v[24:27]
	v_mfma_f32_16x16x32_bf16 v[12:15], v[64:67], v[238:241], v[12:15]
	v_mfma_f32_16x16x32_bf16 v[8:11], v[72:75], v[238:241], v[8:11]
	v_mfma_f32_16x16x32_bf16 v[60:63], v[68:71], v[180:183], v[60:63]
	v_mfma_f32_16x16x32_bf16 v[56:59], v[76:79], v[180:183], v[56:59]
	v_mfma_f32_16x16x32_bf16 v[44:47], v[68:71], v[194:197], v[44:47]
	v_mfma_f32_16x16x32_bf16 v[40:43], v[76:79], v[194:197], v[40:43]
	v_mfma_f32_16x16x32_bf16 v[28:31], v[68:71], v[234:237], v[28:31]
	v_mfma_f32_16x16x32_bf16 v[24:27], v[76:79], v[234:237], v[24:27]
	v_mfma_f32_16x16x32_bf16 v[12:15], v[68:71], v[242:245], v[12:15]
	v_mfma_f32_16x16x32_bf16 v[8:11], v[76:79], v[242:245], v[8:11]
	s_setprio 0
	s_setprio 1
	v_mfma_f32_16x16x32_bf16 v[52:55], v[154:157], v[176:179], v[52:55]
	v_mfma_f32_16x16x32_bf16 v[48:51], v[168:171], v[176:179], v[48:51]
	v_mfma_f32_16x16x32_bf16 v[36:39], v[154:157], v[184:187], v[36:39]
	v_mfma_f32_16x16x32_bf16 v[32:35], v[168:171], v[184:187], v[32:35]
	v_mfma_f32_16x16x32_bf16 v[20:23], v[154:157], v[230:233], v[20:23]
	v_mfma_f32_16x16x32_bf16 v[16:19], v[168:171], v[230:233], v[16:19]
	v_mfma_f32_16x16x32_bf16 v[4:7], v[154:157], v[238:241], v[4:7]
	v_mfma_f32_16x16x32_bf16 v[0:3], v[168:171], v[238:241], v[0:3]
	v_mfma_f32_16x16x32_bf16 v[52:55], v[164:167], v[180:183], v[52:55]
	v_mfma_f32_16x16x32_bf16 v[48:51], v[172:175], v[180:183], v[48:51]
	v_mfma_f32_16x16x32_bf16 v[36:39], v[164:167], v[194:197], v[36:39]
	v_mfma_f32_16x16x32_bf16 v[32:35], v[172:175], v[194:197], v[32:35]
	v_mfma_f32_16x16x32_bf16 v[20:23], v[164:167], v[234:237], v[20:23]
	v_mfma_f32_16x16x32_bf16 v[16:19], v[172:175], v[234:237], v[16:19]
	v_mfma_f32_16x16x32_bf16 v[4:7], v[164:167], v[242:245], v[4:7]
	v_mfma_f32_16x16x32_bf16 v[0:3], v[172:175], v[242:245], v[0:3]
	s_setprio 0
	s_barrier
	s_add_i32 s60, 0, 0x18000
	s_add_i32 s61, 0, 0x1c000
	v_add_u32_e32 v76, s60, v162
	v_add_u32_e32 v172, s61, v162
	ds_read_b128 v[64:67], v76
	ds_read_b128 v[68:71], v76 offset:1024
	ds_read_b128 v[72:75], v76 offset:2048
	ds_read_b128 v[76:79], v76 offset:3072
	ds_read_b128 v[154:157], v172
	ds_read_b128 v[164:167], v172 offset:1024
	ds_read_b128 v[168:171], v172 offset:2048
	ds_read_b128 v[172:175], v172 offset:3072
	s_add_u32 s52, s52, 0x40000
	s_addc_u32 s53, s53, 0
	s_mov_b32 m0, s81
	v_lshl_add_u64 v[252:253], s[52:53], 0, v[144:145]
	ds_read_b128 v[176:179], v163 offset:32768
	ds_read_b128 v[180:183], v163 offset:33792
	ds_read_b128 v[184:187], v163 offset:34816
	ds_read_b128 v[194:197], v163 offset:35840
	ds_read_b128 v[230:233], v163 offset:36864
	ds_read_b128 v[234:237], v163 offset:37888
	ds_read_b128 v[238:241], v163 offset:38912
	ds_read_b128 v[242:245], v163 offset:39936
	global_load_lds_dwordx4 v[252:253], off
	v_lshl_add_u64 v[252:253], s[52:53], 0, v[146:147]
	s_mov_b32 m0, s80
	s_nop 0
	global_load_lds_dwordx4 v[252:253], off
	s_waitcnt vmcnt(8)
	s_waitcnt lgkmcnt(0)
	s_barrier
	s_setprio 1
	s_waitcnt lgkmcnt(0)
	v_mfma_f32_16x16x32_bf16 v[140:143], v[64:67], v[176:179], v[140:143]
	v_mfma_f32_16x16x32_bf16 v[136:139], v[72:75], v[176:179], v[136:139]
	v_mfma_f32_16x16x32_bf16 v[124:127], v[64:67], v[184:187], v[124:127]
	v_mfma_f32_16x16x32_bf16 v[120:123], v[72:75], v[184:187], v[120:123]
	v_mfma_f32_16x16x32_bf16 v[108:111], v[64:67], v[230:233], v[108:111]
	v_mfma_f32_16x16x32_bf16 v[104:107], v[72:75], v[230:233], v[104:107]
	v_mfma_f32_16x16x32_bf16 v[92:95], v[64:67], v[238:241], v[92:95]
	v_mfma_f32_16x16x32_bf16 v[88:91], v[72:75], v[238:241], v[88:91]
	v_mfma_f32_16x16x32_bf16 v[140:143], v[68:71], v[180:183], v[140:143]
	v_mfma_f32_16x16x32_bf16 v[136:139], v[76:79], v[180:183], v[136:139]
	v_mfma_f32_16x16x32_bf16 v[124:127], v[68:71], v[194:197], v[124:127]
	v_mfma_f32_16x16x32_bf16 v[120:123], v[76:79], v[194:197], v[120:123]
	v_mfma_f32_16x16x32_bf16 v[108:111], v[68:71], v[234:237], v[108:111]
	v_mfma_f32_16x16x32_bf16 v[104:107], v[76:79], v[234:237], v[104:107]
	v_mfma_f32_16x16x32_bf16 v[92:95], v[68:71], v[242:245], v[92:95]
	v_mfma_f32_16x16x32_bf16 v[88:91], v[76:79], v[242:245], v[88:91]
	s_setprio 0
	s_setprio 1
	v_mfma_f32_16x16x32_bf16 v[132:135], v[154:157], v[176:179], v[132:135]
	v_mfma_f32_16x16x32_bf16 v[128:131], v[168:171], v[176:179], v[128:131]
	v_mfma_f32_16x16x32_bf16 v[116:119], v[154:157], v[184:187], v[116:119]
	v_mfma_f32_16x16x32_bf16 v[112:115], v[168:171], v[184:187], v[112:115]
	v_mfma_f32_16x16x32_bf16 v[100:103], v[154:157], v[230:233], v[100:103]
	v_mfma_f32_16x16x32_bf16 v[96:99], v[168:171], v[230:233], v[96:99]
	v_mfma_f32_16x16x32_bf16 v[84:87], v[154:157], v[238:241], v[84:87]
	v_mfma_f32_16x16x32_bf16 v[80:83], v[168:171], v[238:241], v[80:83]
	v_mfma_f32_16x16x32_bf16 v[132:135], v[164:167], v[180:183], v[132:135]
	v_mfma_f32_16x16x32_bf16 v[128:131], v[172:175], v[180:183], v[128:131]
	v_mfma_f32_16x16x32_bf16 v[116:119], v[164:167], v[194:197], v[116:119]
	v_mfma_f32_16x16x32_bf16 v[112:115], v[172:175], v[194:197], v[112:115]
	v_mfma_f32_16x16x32_bf16 v[100:103], v[164:167], v[234:237], v[100:103]
	v_mfma_f32_16x16x32_bf16 v[96:99], v[172:175], v[234:237], v[96:99]
	v_mfma_f32_16x16x32_bf16 v[84:87], v[164:167], v[242:245], v[84:87]
	v_mfma_f32_16x16x32_bf16 v[80:83], v[172:175], v[242:245], v[80:83]
	s_setprio 0
	s_barrier
; #define PG8_STAGE(bufoff, gbase, voff) do { _Pragma("unroll") for (int _i = 0; _i < 2; ++_i) \
;         __builtin_amdgcn_global_load_lds((const unsigned*)((const char*)(gbase) + (voff)[_i]), (PG8_LAS unsigned*)(lds + (bufoff) + ldsw + _i * 8192), 16, 0, 0); } while (0)
; #define PG8_LDA(dst, b, h) do { _Pragma("unroll") for (int m = 0; m < 4; ++m) _Pragma("unroll") for (int k = 0; k < 2; ++k) dst[m][k] = *(const PG8_LAS bf16x8*)(lds + PG8_SA(b, h) + aoff + m * 2048 + k * 1024); } while (0)
; #define PG8_MMA(ai, bj, At, Bt) do { __builtin_amdgcn_s_setprio(1); _Pragma("unroll") for (int m = 0; m < 4; ++m) _Pragma("unroll") for (int n = 0; n < 2; ++n) _Pragma("unroll") for (int k = 0; k < 2; ++k) \
;         acc[ai][bj][m][n] = __builtin_amdgcn_mfma_f32_16x16x32_bf16(Bt[n][k], At[m][k], acc[ai][bj][m][n], 0, 0, 0); __builtin_amdgcn_s_setprio(0); } while (0)
; #define PG8_WAIT_V(n) asm volatile("s_waitcnt vmcnt(" #n ")" ::: "memory")
; #define PG8_WAIT_L(n) asm volatile("s_waitcnt lgkmcnt(" #n ")" ::: "memory")
; #define PG8_BAR __builtin_amdgcn_s_barrier()
; #define PG8_SCHED __builtin_amdgcn_sched_barrier(0)
; template <class Epi, class Sched, bool ALIGN_EPI = false, bool SP2 = false>
; __device__ __forceinline__ void gemm_phase(PG8_LAS unsigned char* lds, const Gemm g, const Sched& S, const Epi& E) {
;     ...
;             PG8_LDA(At, 1, 1); PG8_STAGE(PG8_SB(1, 0), b3, voffB); PG8_STAGE(PG8_SB(1, 1), b3 + hstepB, voffB); PG8_STAGE(PG8_SA(1, 0), a3, voffA);
;             PG8_WAIT_V(8); PG8_WAIT_L(0); PG8_BAR; PG8_MMA(1, 0, At, B0); PG8_MMA(1, 1, At, B1); PG8_BAR; PG8_SCHED;
;     ...
;         if constexpr (ALIGN_EPI) { if (wr == 0) PG8_BAR; }
	s_add_i32 s52, s60, s69
	v_lshl_add_u64 v[158:159], v[158:159], 0, s[94:95]
	s_mov_b32 m0, s52
	ds_read_b128 v[176:179], v163 offset:49152
	ds_read_b128 v[180:183], v163 offset:50176
	ds_read_b128 v[184:187], v163 offset:51200
	ds_read_b128 v[194:197], v163 offset:52224
	ds_read_b128 v[230:233], v163 offset:53248
	ds_read_b128 v[234:237], v163 offset:54272
	ds_read_b128 v[238:241], v163 offset:55296
	ds_read_b128 v[242:245], v163 offset:56320
	global_load_lds_dwordx4 v[158:159], off
	s_add_i32 m0, s52, 0x2000
	s_add_u32 s50, s50, 0x40080
	v_lshl_add_u64 v[158:159], v[246:247], 0, s[94:95]
	s_addc_u32 s51, s51, 0
	s_add_i32 s52, s61, s69
	global_load_lds_dwordx4 v[158:159], off
	v_lshl_add_u64 v[158:159], s[50:51], 0, v[188:189]
	s_mov_b32 m0, s52
	s_nop 0
	global_load_lds_dwordx4 v[158:159], off
	v_lshl_add_u64 v[158:159], s[50:51], 0, v[148:149]
	s_add_i32 m0, s52, 0x2000
	s_nop 0
	global_load_lds_dwordx4 v[158:159], off
	v_lshl_add_u64 v[158:159], v[248:249], 0, s[94:95]
	s_mov_b32 m0, s2
	s_nop 0
	global_load_lds_dwordx4 v[158:159], off
	v_lshl_add_u64 v[158:159], v[250:251], 0, s[94:95]
	s_mov_b32 m0, s4
	s_nop 0
	global_load_lds_dwordx4 v[158:159], off
	s_waitcnt vmcnt(8)
	s_waitcnt lgkmcnt(0)
	s_barrier
	s_setprio 1
	s_waitcnt lgkmcnt(0)
	v_mfma_f32_16x16x32_bf16 v[60:63], v[64:67], v[176:179], v[60:63]
	v_mfma_f32_16x16x32_bf16 v[56:59], v[72:75], v[176:179], v[56:59]
	v_mfma_f32_16x16x32_bf16 v[44:47], v[64:67], v[184:187], v[44:47]
	v_mfma_f32_16x16x32_bf16 v[40:43], v[72:75], v[184:187], v[40:43]
	v_mfma_f32_16x16x32_bf16 v[28:31], v[64:67], v[230:233], v[28:31]
	v_mfma_f32_16x16x32_bf16 v[24:27], v[72:75], v[230:233], v[24:27]
	v_mfma_f32_16x16x32_bf16 v[12:15], v[64:67], v[238:241], v[12:15]
	v_mfma_f32_16x16x32_bf16 v[8:11], v[72:75], v[238:241], v[8:11]
	v_mfma_f32_16x16x32_bf16 v[60:63], v[68:71], v[180:183], v[60:63]
	v_mfma_f32_16x16x32_bf16 v[56:59], v[76:79], v[180:183], v[56:59]
	v_mfma_f32_16x16x32_bf16 v[44:47], v[68:71], v[194:197], v[44:47]
	v_mfma_f32_16x16x32_bf16 v[40:43], v[76:79], v[194:197], v[40:43]
	v_mfma_f32_16x16x32_bf16 v[28:31], v[68:71], v[234:237], v[28:31]
	v_mfma_f32_16x16x32_bf16 v[24:27], v[76:79], v[234:237], v[24:27]
	v_mfma_f32_16x16x32_bf16 v[12:15], v[68:71], v[242:245], v[12:15]
	v_mfma_f32_16x16x32_bf16 v[8:11], v[76:79], v[242:245], v[8:11]
	s_setprio 0
	s_setprio 1
	v_mfma_f32_16x16x32_bf16 v[52:55], v[154:157], v[176:179], v[52:55]
	v_mfma_f32_16x16x32_bf16 v[48:51], v[168:171], v[176:179], v[48:51]
	v_mfma_f32_16x16x32_bf16 v[36:39], v[154:157], v[184:187], v[36:39]
	v_mfma_f32_16x16x32_bf16 v[32:35], v[168:171], v[184:187], v[32:35]
	v_mfma_f32_16x16x32_bf16 v[20:23], v[154:157], v[230:233], v[20:23]
	v_mfma_f32_16x16x32_bf16 v[16:19], v[168:171], v[230:233], v[16:19]
	v_mfma_f32_16x16x32_bf16 v[4:7], v[154:157], v[238:241], v[4:7]
	v_mfma_f32_16x16x32_bf16 v[0:3], v[168:171], v[238:241], v[0:3]
	v_mfma_f32_16x16x32_bf16 v[52:55], v[164:167], v[180:183], v[52:55]
	v_mfma_f32_16x16x32_bf16 v[48:51], v[172:175], v[180:183], v[48:51]
	v_mfma_f32_16x16x32_bf16 v[36:39], v[164:167], v[194:197], v[36:39]
	v_mfma_f32_16x16x32_bf16 v[32:35], v[172:175], v[194:197], v[32:35]
	v_mfma_f32_16x16x32_bf16 v[20:23], v[164:167], v[234:237], v[20:23]
	v_mfma_f32_16x16x32_bf16 v[16:19], v[172:175], v[234:237], v[16:19]
	v_mfma_f32_16x16x32_bf16 v[4:7], v[164:167], v[242:245], v[4:7]
	v_mfma_f32_16x16x32_bf16 v[0:3], v[172:175], v[242:245], v[0:3]
	s_setprio 0
	s_barrier
	s_add_i32 s59, s59, 2
	s_add_u32 s8, s8, 0x100
	s_addc_u32 s9, s9, 0
	s_add_u32 s55, s55, 0x100
	s_addc_u32 s58, s58, 0
	s_cmp_gt_u32 s59, 13
	s_cbranch_scc0 .LBB0_171
	s_and_b64 vcc, exec, s[30:31]
	s_cbranch_vccz .LBB0_174
	s_barrier

; template <class Epi, class Sched, bool ALIGN_EPI = false, bool SP2 = false>
; __device__ __forceinline__ void gemm_phase(PG8_LAS unsigned char* lds, const Gemm g, const Sched& S, const Epi& E) {
;     ...
;         if (!has_next) break;
; #pragma unroll
;         for (int a = 0; a < 2; ++a)
; #pragma unroll
;             for (int b = 0; b < 2; ++b)
; #pragma unroll
;                 for (int m = 0; m < 4; ++m)
; #pragma unroll
;                     for (int n = 0; n < 2; ++n) acc[a][b][m][n] = (f32x4){0.f, 0.f, 0.f, 0.f};
;         cur = nxt; cA = nA; cB = nB; ++ui;
.LBB0_1641:
	s_add_u32 s26, s26, 0x80
	s_addc_u32 s27, s27, 0
	s_add_u32 s72, s28, 0x100
	v_mov_b32_e32 v0, 0
	s_addc_u32 s73, s29, 0
	s_mov_b32 s28, 0
	v_mov_b32_e32 v1, v0
	v_mov_b32_e32 v2, v0
	v_mov_b32_e32 v3, v0
	v_mov_b32_e32 v16, v0
	v_mov_b32_e32 v17, v0
	v_mov_b32_e32 v18, v0
	v_mov_b32_e32 v19, v0
	v_mov_b32_e32 v4, v0
	v_mov_b32_e32 v5, v0
	v_mov_b32_e32 v6, v0
	v_mov_b32_e32 v7, v0
	v_mov_b32_e32 v24, v0
	v_mov_b32_e32 v25, v0
	v_mov_b32_e32 v26, v0
	v_mov_b32_e32 v27, v0
	v_mov_b32_e32 v8, v0
	v_mov_b32_e32 v9, v0
	v_mov_b32_e32 v10, v0
	v_mov_b32_e32 v11, v0
	v_mov_b32_e32 v32, v0
	v_mov_b32_e32 v33, v0
	v_mov_b32_e32 v34, v0
	v_mov_b32_e32 v35, v0
	v_mov_b32_e32 v12, v0
	v_mov_b32_e32 v13, v0
	v_mov_b32_e32 v14, v0
	v_mov_b32_e32 v15, v0
	v_mov_b32_e32 v40, v0
	v_mov_b32_e32 v41, v0
	v_mov_b32_e32 v42, v0
	v_mov_b32_e32 v43, v0
	v_mov_b32_e32 v52, v0
	v_mov_b32_e32 v53, v0
	v_mov_b32_e32 v54, v0
	v_mov_b32_e32 v55, v0
	v_mov_b32_e32 v84, v0
	v_mov_b32_e32 v85, v0
	v_mov_b32_e32 v86, v0
	v_mov_b32_e32 v87, v0
	v_mov_b32_e32 v60, v0
	v_mov_b32_e32 v61, v0
	v_mov_b32_e32 v62, v0
	v_mov_b32_e32 v63, v0
	v_mov_b32_e32 v100, v0
	v_mov_b32_e32 v101, v0
	v_mov_b32_e32 v102, v0
	v_mov_b32_e32 v103, v0
	v_mov_b32_e32 v68, v0
	v_mov_b32_e32 v69, v0
	v_mov_b32_e32 v70, v0
	v_mov_b32_e32 v71, v0
	v_mov_b32_e32 v104, v0
	v_mov_b32_e32 v105, v0
	v_mov_b32_e32 v106, v0
	v_mov_b32_e32 v107, v0
	v_mov_b32_e32 v76, v0
	v_mov_b32_e32 v77, v0
	v_mov_b32_e32 v78, v0
	v_mov_b32_e32 v79, v0
	v_mov_b32_e32 v108, v0
	v_mov_b32_e32 v109, v0
	v_mov_b32_e32 v110, v0
	v_mov_b32_e32 v111, v0
	v_mov_b32_e32 v20, v0
	v_mov_b32_e32 v21, v0
	v_mov_b32_e32 v22, v0
	v_mov_b32_e32 v23, v0
	v_mov_b32_e32 v48, v0
	v_mov_b32_e32 v49, v0
	v_mov_b32_e32 v50, v0
	v_mov_b32_e32 v51, v0
	v_mov_b32_e32 v28, v0
	v_mov_b32_e32 v29, v0
	v_mov_b32_e32 v30, v0
	v_mov_b32_e32 v31, v0
	v_mov_b32_e32 v56, v0
	v_mov_b32_e32 v57, v0
	v_mov_b32_e32 v58, v0
	v_mov_b32_e32 v59, v0
	v_mov_b32_e32 v36, v0
	v_mov_b32_e32 v37, v0
	v_mov_b32_e32 v38, v0
	v_mov_b32_e32 v39, v0
	v_mov_b32_e32 v64, v0
	v_mov_b32_e32 v65, v0
	v_mov_b32_e32 v66, v0
	v_mov_b32_e32 v67, v0
	v_mov_b32_e32 v44, v0
	v_mov_b32_e32 v45, v0
	v_mov_b32_e32 v46, v0
	v_mov_b32_e32 v47, v0
	v_mov_b32_e32 v72, v0
	v_mov_b32_e32 v73, v0
	v_mov_b32_e32 v74, v0
	v_mov_b32_e32 v75, v0
	v_mov_b32_e32 v80, v0
	v_mov_b32_e32 v81, v0
	v_mov_b32_e32 v82, v0
	v_mov_b32_e32 v83, v0
	v_mov_b32_e32 v112, v0
	v_mov_b32_e32 v113, v0
	v_mov_b32_e32 v114, v0
	v_mov_b32_e32 v115, v0
	v_mov_b32_e32 v88, v0
	v_mov_b32_e32 v89, v0
	v_mov_b32_e32 v90, v0
	v_mov_b32_e32 v91, v0
	v_mov_b32_e32 v116, v0
	v_mov_b32_e32 v117, v0
	v_mov_b32_e32 v118, v0
	v_mov_b32_e32 v119, v0
	v_mov_b32_e32 v92, v0
	v_mov_b32_e32 v93, v0
	v_mov_b32_e32 v94, v0
	v_mov_b32_e32 v95, v0
	v_mov_b32_e32 v120, v0
	v_mov_b32_e32 v121, v0
	v_mov_b32_e32 v122, v0
	v_mov_b32_e32 v123, v0
	v_mov_b32_e32 v96, v0
	v_mov_b32_e32 v97, v0
	v_mov_b32_e32 v98, v0
	v_mov_b32_e32 v99, v0
	v_mov_b32_e32 v124, v0
	v_mov_b32_e32 v125, v0
	v_mov_b32_e32 v126, v0
	v_mov_b32_e32 v127, v0

; template <class Epi, class Sched, bool ALIGN_EPI = false, bool SP2 = false>
; __device__ __forceinline__ void gemm_phase(PG8_LAS unsigned char* lds, const Gemm g, const Sched& S, const Epi& E) {
;     ...
;         const bool has_next = S.next(ui + 1, nxt);
;         const char* nA = has_next ? (const char*)g.A + (size_t)nxt.pm * tstepA + (size_t)((nxt.pn / g.kdiv) * g.kmul) * 2 : cA; const char* nB = has_next ? (const char*)g.Bt + (size_t)nxt.pn * tstepB : cB;
;     ...
; #pragma unroll
;         for (int a = 0; a < 2; ++a)
; #pragma unroll
;             for (int b = 0; b < 2; ++b)
; #pragma unroll
;                 for (int m = 0; m < 4; ++m)
; #pragma unroll
;                     for (int n = 0; n < 2; ++n) acc[a][b][m][n] = (f32x4){0.f, 0.f, 0.f, 0.f};
;         cur = nxt; cA = nA; cB = nB; ++ui;
.LBB0_1799:
	s_ashr_i32 s37, s36, 31
	s_lshl_b64 s[8:9], s[36:37], 19
	s_add_u32 s40, s33, s8
	s_addc_u32 s41, s50, s9
	s_and_b64 s[8:9], s[6:7], exec
	s_cselect_b32 s13, s41, s47
	s_cselect_b32 s15, s40, s46
	s_ashr_i32 s35, s34, 31
	s_lshl_b64 s[8:9], s[34:35], 19
	s_add_u32 s42, s51, s8
	s_addc_u32 s43, s52, s9
	s_and_b64 s[8:9], s[6:7], exec
	s_cselect_b32 s35, s43, s45
	s_cselect_b32 s37, s42, s44
	s_add_u32 s8, s46, 0x40080
	s_addc_u32 s9, s47, 0
	s_add_u32 s46, s44, 0x100
	v_mov_b32_e32 v0, 0
	s_addc_u32 s47, s45, 0
	s_mov_b32 s70, -2
	v_mov_b32_e32 v1, v0
	v_mov_b32_e32 v2, v0
	v_mov_b32_e32 v3, v0
	v_mov_b32_e32 v64, v0
	v_mov_b32_e32 v65, v0
	v_mov_b32_e32 v66, v0
	v_mov_b32_e32 v67, v0
	v_mov_b32_e32 v20, v0
	v_mov_b32_e32 v21, v0
	v_mov_b32_e32 v22, v0
	v_mov_b32_e32 v23, v0
	v_mov_b32_e32 v84, v0
	v_mov_b32_e32 v85, v0
	v_mov_b32_e32 v86, v0
	v_mov_b32_e32 v87, v0
	v_mov_b32_e32 v4, v0
	v_mov_b32_e32 v5, v0
	v_mov_b32_e32 v6, v0
	v_mov_b32_e32 v7, v0
	v_mov_b32_e32 v28, v0
	v_mov_b32_e32 v29, v0
	v_mov_b32_e32 v30, v0
	v_mov_b32_e32 v31, v0
	v_mov_b32_e32 v32, v0
	v_mov_b32_e32 v33, v0
	v_mov_b32_e32 v34, v0
	v_mov_b32_e32 v35, v0
	v_mov_b32_e32 v96, v0
	v_mov_b32_e32 v97, v0
	v_mov_b32_e32 v98, v0
	v_mov_b32_e32 v99, v0
	v_mov_b32_e32 v52, v0
	v_mov_b32_e32 v53, v0
	v_mov_b32_e32 v54, v0
	v_mov_b32_e32 v55, v0
	v_mov_b32_e32 v116, v0
	v_mov_b32_e32 v117, v0
	v_mov_b32_e32 v118, v0
	v_mov_b32_e32 v119, v0
	v_mov_b32_e32 v36, v0
	v_mov_b32_e32 v37, v0
	v_mov_b32_e32 v38, v0
	v_mov_b32_e32 v39, v0
	v_mov_b32_e32 v60, v0
	v_mov_b32_e32 v61, v0
	v_mov_b32_e32 v62, v0
	v_mov_b32_e32 v63, v0
	v_mov_b32_e32 v124, v0
	v_mov_b32_e32 v125, v0
	v_mov_b32_e32 v126, v0
	v_mov_b32_e32 v127, v0
	v_mov_b32_e32 v100, v0
	v_mov_b32_e32 v101, v0
	v_mov_b32_e32 v102, v0
	v_mov_b32_e32 v103, v0
	v_mov_b32_e32 v92, v0
	v_mov_b32_e32 v93, v0
	v_mov_b32_e32 v94, v0
	v_mov_b32_e32 v95, v0
	v_mov_b32_e32 v68, v0
	v_mov_b32_e32 v69, v0
	v_mov_b32_e32 v70, v0
	v_mov_b32_e32 v71, v0
	v_mov_b32_e32 v8, v0
	v_mov_b32_e32 v9, v0
	v_mov_b32_e32 v10, v0
	v_mov_b32_e32 v11, v0
	v_mov_b32_e32 v72, v0
	v_mov_b32_e32 v73, v0
	v_mov_b32_e32 v74, v0
	v_mov_b32_e32 v75, v0
	v_mov_b32_e32 v16, v0
	v_mov_b32_e32 v17, v0
	v_mov_b32_e32 v18, v0
	v_mov_b32_e32 v19, v0
	v_mov_b32_e32 v80, v0
	v_mov_b32_e32 v81, v0
	v_mov_b32_e32 v82, v0
	v_mov_b32_e32 v83, v0
	v_mov_b32_e32 v12, v0
	v_mov_b32_e32 v13, v0
	v_mov_b32_e32 v14, v0
	v_mov_b32_e32 v15, v0
	v_mov_b32_e32 v76, v0
	v_mov_b32_e32 v77, v0
	v_mov_b32_e32 v78, v0
	v_mov_b32_e32 v79, v0
	v_mov_b32_e32 v24, v0
	v_mov_b32_e32 v25, v0
	v_mov_b32_e32 v26, v0
	v_mov_b32_e32 v27, v0
	v_mov_b32_e32 v88, v0
	v_mov_b32_e32 v89, v0
	v_mov_b32_e32 v90, v0
	v_mov_b32_e32 v91, v0
	v_mov_b32_e32 v40, v0
	v_mov_b32_e32 v41, v0
	v_mov_b32_e32 v42, v0
	v_mov_b32_e32 v43, v0
	v_mov_b32_e32 v104, v0
	v_mov_b32_e32 v105, v0
	v_mov_b32_e32 v106, v0
	v_mov_b32_e32 v107, v0
	v_mov_b32_e32 v48, v0
	v_mov_b32_e32 v49, v0
	v_mov_b32_e32 v50, v0
	v_mov_b32_e32 v51, v0
	v_mov_b32_e32 v112, v0
	v_mov_b32_e32 v113, v0
	v_mov_b32_e32 v114, v0
	v_mov_b32_e32 v115, v0
	v_mov_b32_e32 v44, v0
	v_mov_b32_e32 v45, v0
	v_mov_b32_e32 v46, v0
	v_mov_b32_e32 v47, v0
	v_mov_b32_e32 v108, v0
	v_mov_b32_e32 v109, v0
	v_mov_b32_e32 v110, v0
	v_mov_b32_e32 v111, v0
	v_mov_b32_e32 v56, v0
	v_mov_b32_e32 v57, v0
	v_mov_b32_e32 v58, v0
	v_mov_b32_e32 v59, v0
	v_mov_b32_e32 v120, v0
	v_mov_b32_e32 v121, v0
	v_mov_b32_e32 v122, v0
	v_mov_b32_e32 v123, v0

; template <class Epi, class Sched, bool ALIGN_EPI = false, bool SP2 = false>
; __device__ __forceinline__ void gemm_phase(PG8_LAS unsigned char* lds, const Gemm g, const Sched& S, const Epi& E) {
;     ...
; #pragma unroll
;         for (int a = 0; a < 2; ++a)
; #pragma unroll
;             for (int b = 0; b < 2; ++b)
; #pragma unroll
;                 for (int m = 0; m < 4; ++m)
; #pragma unroll
;                     for (int n = 0; n < 2; ++n) acc[a][b][m][n] = (f32x4){0.f, 0.f, 0.f, 0.f};
;         cur = nxt; cA = nA; cB = nB; ++ui;
.LBB0_1992:
	s_add_u32 s65, s24, 0x100
	v_mov_b32_e32 v0, 0
	s_addc_u32 s66, s25, 0
	s_mov_b32 s67, -2
	v_mov_b32_e32 v1, v0
	v_mov_b32_e32 v2, v0
	v_mov_b32_e32 v3, v0
	v_mov_b32_e32 v28, v0
	v_mov_b32_e32 v29, v0
	v_mov_b32_e32 v30, v0
	v_mov_b32_e32 v31, v0
	v_mov_b32_e32 v4, v0
	v_mov_b32_e32 v5, v0
	v_mov_b32_e32 v6, v0
	v_mov_b32_e32 v7, v0
	v_mov_b32_e32 v32, v0
	v_mov_b32_e32 v33, v0
	v_mov_b32_e32 v34, v0
	v_mov_b32_e32 v35, v0
	v_mov_b32_e32 v8, v0
	v_mov_b32_e32 v9, v0
	v_mov_b32_e32 v10, v0
	v_mov_b32_e32 v11, v0
	v_mov_b32_e32 v40, v0
	v_mov_b32_e32 v41, v0
	v_mov_b32_e32 v42, v0
	v_mov_b32_e32 v43, v0
	v_mov_b32_e32 v12, v0
	v_mov_b32_e32 v13, v0
	v_mov_b32_e32 v14, v0
	v_mov_b32_e32 v15, v0
	v_mov_b32_e32 v44, v0
	v_mov_b32_e32 v45, v0
	v_mov_b32_e32 v46, v0
	v_mov_b32_e32 v47, v0
	v_mov_b32_e32 v60, v0
	v_mov_b32_e32 v61, v0
	v_mov_b32_e32 v62, v0
	v_mov_b32_e32 v63, v0
	v_mov_b32_e32 v88, v0
	v_mov_b32_e32 v89, v0
	v_mov_b32_e32 v90, v0
	v_mov_b32_e32 v91, v0
	v_mov_b32_e32 v68, v0
	v_mov_b32_e32 v69, v0
	v_mov_b32_e32 v70, v0
	v_mov_b32_e32 v71, v0
	v_mov_b32_e32 v100, v0
	v_mov_b32_e32 v101, v0
	v_mov_b32_e32 v102, v0
	v_mov_b32_e32 v103, v0
	v_mov_b32_e32 v72, v0
	v_mov_b32_e32 v73, v0
	v_mov_b32_e32 v74, v0
	v_mov_b32_e32 v75, v0
	v_mov_b32_e32 v104, v0
	v_mov_b32_e32 v105, v0
	v_mov_b32_e32 v106, v0
	v_mov_b32_e32 v107, v0
	v_mov_b32_e32 v76, v0
	v_mov_b32_e32 v77, v0
	v_mov_b32_e32 v78, v0
	v_mov_b32_e32 v79, v0
	v_mov_b32_e32 v108, v0
	v_mov_b32_e32 v109, v0
	v_mov_b32_e32 v110, v0
	v_mov_b32_e32 v111, v0
	v_mov_b32_e32 v16, v0
	v_mov_b32_e32 v17, v0
	v_mov_b32_e32 v18, v0
	v_mov_b32_e32 v19, v0
	v_mov_b32_e32 v48, v0
	v_mov_b32_e32 v49, v0
	v_mov_b32_e32 v50, v0
	v_mov_b32_e32 v51, v0
	v_mov_b32_e32 v20, v0
	v_mov_b32_e32 v21, v0
	v_mov_b32_e32 v22, v0
	v_mov_b32_e32 v23, v0
	v_mov_b32_e32 v52, v0
	v_mov_b32_e32 v53, v0
	v_mov_b32_e32 v54, v0
	v_mov_b32_e32 v55, v0
	v_mov_b32_e32 v24, v0
	v_mov_b32_e32 v25, v0
	v_mov_b32_e32 v26, v0
	v_mov_b32_e32 v27, v0
	v_mov_b32_e32 v56, v0
	v_mov_b32_e32 v57, v0
	v_mov_b32_e32 v58, v0
	v_mov_b32_e32 v59, v0
	v_mov_b32_e32 v36, v0
	v_mov_b32_e32 v37, v0
	v_mov_b32_e32 v38, v0
	v_mov_b32_e32 v39, v0
	v_mov_b32_e32 v64, v0
	v_mov_b32_e32 v65, v0
	v_mov_b32_e32 v66, v0
	v_mov_b32_e32 v67, v0
	v_mov_b32_e32 v80, v0
	v_mov_b32_e32 v81, v0
	v_mov_b32_e32 v82, v0
	v_mov_b32_e32 v83, v0
	v_mov_b32_e32 v112, v0
	v_mov_b32_e32 v113, v0
	v_mov_b32_e32 v114, v0
	v_mov_b32_e32 v115, v0
	v_mov_b32_e32 v84, v0
	v_mov_b32_e32 v85, v0
	v_mov_b32_e32 v86, v0
	v_mov_b32_e32 v87, v0
	v_mov_b32_e32 v116, v0
	v_mov_b32_e32 v117, v0
	v_mov_b32_e32 v118, v0
	v_mov_b32_e32 v119, v0
	v_mov_b32_e32 v92, v0
	v_mov_b32_e32 v93, v0
	v_mov_b32_e32 v94, v0
	v_mov_b32_e32 v95, v0
	v_mov_b32_e32 v120, v0
	v_mov_b32_e32 v121, v0
	v_mov_b32_e32 v122, v0
	v_mov_b32_e32 v123, v0
	v_mov_b32_e32 v96, v0
	v_mov_b32_e32 v97, v0
	v_mov_b32_e32 v98, v0
	v_mov_b32_e32 v99, v0
	v_mov_b32_e32 v124, v0
	v_mov_b32_e32 v125, v0
	v_mov_b32_e32 v126, v0
	v_mov_b32_e32 v127, v0
